# attention steady loop: LDS read addresses for the post-barrier fragment reads computed ahead of the barriers (on top of back-edge rotation and P11 pipelining)
# speedup vs baseline: 1.0003x; 1.0000x over previous
.LBB0_514:
	s_lshl_b32 s4, s0, 8
	s_add_i32 s4, s4, 0
	s_add_i32 s4, s4, 0x14800
	v_lshl_add_u32 v49, v232, 4, s4
	s_lshl_b32 s4, s0, 6
	s_addk_i32 s4, 0x7b
	v_add_u32_e32 v50, s4, v222
	s_lshl_b64 s[4:5], s[0:1], 16
	v_subrev_u32_e32 v216, s52, v50
	v_lshl_add_u64 v[50:51], v[224:225], 0, s[4:5]
	s_add_i32 s74, s71, -2
	s_sub_i32 s75, 0, s71
	s_add_i32 s76, s0, 2
	v_lshl_add_u64 v[212:213], v[226:227], 0, s[4:5]
	v_lshl_add_u64 v[214:215], v[50:51], 0, s[40:41]
	v_add_u32_e32 v52, s53, v243
.LBB0_515:
	ds_read_b64_tr_b16 v[204:205], v52 offset:24576
	ds_read_b64_tr_b16 v[206:207], v52 offset:25088
	s_waitcnt lgkmcnt(9)
	v_mfma_f32_32x32x16_bf16 v[96:111], v[114:117], v[140:143], v[32:47]
	v_add_f32_e32 v50, v80, v81
	v_add_f32_e32 v50, v82, v50
	v_add_f32_e32 v50, v83, v50
	v_add_f32_e32 v50, v84, v50
	v_add_f32_e32 v50, v85, v50
	v_cvt_pk_bf16_f32 v156, v80, v81
	v_cvt_pk_bf16_f32 v157, v82, v83
	ds_read_b64_tr_b16 v[200:201], v52 offset:28672
	ds_read_b64_tr_b16 v[202:203], v52 offset:29184
	s_waitcnt lgkmcnt(10)
	v_mfma_f32_32x32x16_bf16 v[112:127], v[184:187], v[140:143], v[32:47]
	v_add_f32_e32 v50, v86, v50
	v_add_f32_e32 v50, v87, v50
	v_add_f32_e32 v50, v88, v50
	v_add_f32_e32 v50, v89, v50
	v_cvt_pk_bf16_f32 v158, v84, v85
	v_cvt_pk_bf16_f32 v159, v86, v87
	ds_read_b64_tr_b16 v[196:197], v52 offset:25600
	ds_read_b64_tr_b16 v[198:199], v52 offset:26112
	s_waitcnt lgkmcnt(11)
	v_mfma_f32_32x32x16_bf16 v[96:111], v[180:183], v[136:139], v[96:111]
	v_add_f32_e32 v50, v90, v50
	v_add_f32_e32 v50, v91, v50
	v_add_f32_e32 v50, v92, v50
	v_add_f32_e32 v50, v93, v50
	v_cvt_pk_bf16_f32 v152, v88, v89
	v_cvt_pk_bf16_f32 v153, v90, v91
	ds_read_b64_tr_b16 v[192:193], v52 offset:29696
	ds_read_b64_tr_b16 v[194:195], v52 offset:30208
	s_waitcnt lgkmcnt(12)
	v_mfma_f32_32x32x16_bf16 v[112:127], v[176:179], v[136:139], v[112:127]
	v_add_f32_e32 v50, v94, v50
	v_add_f32_e32 v50, v95, v50
	v_add_f32_e32 v50, v64, v50
	v_add_f32_e32 v50, v65, v50
	v_cvt_pk_bf16_f32 v154, v92, v93
	v_cvt_pk_bf16_f32 v155, v94, v95
	ds_read_b64_tr_b16 v[188:189], v52 offset:26624
	ds_read_b64_tr_b16 v[190:191], v52 offset:27136
	s_waitcnt lgkmcnt(13)
	v_mfma_f32_32x32x16_bf16 v[96:111], v[172:175], v[132:135], v[96:111]
	v_add_f32_e32 v50, v66, v50
	v_add_f32_e32 v50, v67, v50
	v_add_f32_e32 v50, v68, v50
	v_add_f32_e32 v50, v69, v50
	v_cvt_pk_bf16_f32 v148, v64, v65
	v_cvt_pk_bf16_f32 v149, v66, v67
	ds_read_b64_tr_b16 v[58:59], v52 offset:30720
	ds_read_b64_tr_b16 v[60:61], v52 offset:31232
	s_waitcnt lgkmcnt(14)
	v_mfma_f32_32x32x16_bf16 v[112:127], v[164:167], v[132:135], v[112:127]
	v_add_f32_e32 v50, v70, v50
	v_add_f32_e32 v50, v71, v50
	v_add_f32_e32 v50, v72, v50
	v_add_f32_e32 v50, v73, v50
	v_cvt_pk_bf16_f32 v150, v68, v69
	v_cvt_pk_bf16_f32 v151, v70, v71
	ds_read_b64_tr_b16 v[54:55], v52 offset:27648
	ds_read_b64_tr_b16 v[56:57], v52 offset:28160
	s_waitcnt lgkmcnt(14)
	v_mfma_f32_32x32x16_bf16 v[96:111], v[168:171], v[128:131], v[96:111]
	v_add_f32_e32 v50, v74, v50
	v_add_f32_e32 v50, v75, v50
	v_add_f32_e32 v50, v76, v50
	v_add_f32_e32 v62, v77, v50
	v_cvt_pk_bf16_f32 v144, v72, v73
	v_cvt_pk_bf16_f32 v145, v74, v75
	ds_read_b64_tr_b16 v[50:51], v52 offset:31744
	ds_read_b64_tr_b16 v[52:53], v52 offset:32256
	v_mfma_f32_32x32x16_bf16 v[112:127], v[160:163], v[128:131], v[112:127]
	v_add_f32_e32 v62, v78, v62
	v_add_f32_e32 v62, v79, v62
	v_add_f32_e32 v217, 0, v62
	v_cvt_pk_bf16_f32 v146, v76, v77
	v_cvt_pk_bf16_f32 v147, v78, v79
	s_add_i32 s0, s76, 1
	s_cmp_ge_u32 s0, s71
	s_cselect_b64 s[52:53], -1, 0
	s_and_b64 vcc, exec, s[52:53]
	s_cbranch_vccnz .LBB0_517
	s_add_i32 s0, s72, s69
	v_lshl_add_u64 v[62:63], v[214:215], 0, s[38:39]
	s_mov_b32 s4, m0
	s_mov_b32 m0, s0
	s_nop 0
	global_load_lds_dwordx4 v[62:63], off
	s_mov_b32 m0, s4

.LBB0_519:
	ds_read_b128 v[62:65], v49
	ds_read_b128 v[66:69], v49 offset:128
	ds_read_b128 v[70:73], v49 offset:32
	s_waitcnt lgkmcnt(2)
	v_add_f32_e32 v82, v96, v62
	v_add_f32_e32 v83, v97, v63
	v_add_f32_e32 v84, v98, v64
	v_add_f32_e32 v85, v99, v65
	ds_read_b128 v[62:65], v49 offset:160
	s_waitcnt lgkmcnt(2)
	v_add_f32_e32 v98, v112, v66
	v_add_f32_e32 v99, v113, v67
	v_add_f32_e32 v112, v114, v68
	v_add_f32_e32 v113, v115, v69
	ds_read_b128 v[66:69], v49 offset:64
	s_waitcnt lgkmcnt(2)
	v_pk_add_f32 v[86:87], v[100:101], v[70:71]
	v_pk_add_f32 v[88:89], v[102:103], v[72:73]
	s_waitcnt lgkmcnt(1)
	v_pk_add_f32 v[70:71], v[116:117], v[62:63]
	v_pk_add_f32 v[72:73], v[118:119], v[64:65]
	ds_read_b128 v[62:65], v49 offset:192
	ds_read_b128 v[78:81], v49 offset:96
	s_waitcnt lgkmcnt(2)
	v_pk_add_f32 v[90:91], v[104:105], v[66:67]
	v_pk_add_f32 v[92:93], v[106:107], v[68:69]
	ds_read_b128 v[66:69], v49 offset:224
	s_waitcnt lgkmcnt(2)
	v_pk_add_f32 v[74:75], v[120:121], v[62:63]
	v_pk_add_f32 v[76:77], v[122:123], v[64:65]
	s_waitcnt lgkmcnt(1)
	v_pk_add_f32 v[94:95], v[108:109], v[78:79]
	v_pk_add_f32 v[96:97], v[110:111], v[80:81]
	s_waitcnt lgkmcnt(0)
	v_pk_add_f32 v[78:79], v[124:125], v[66:67]
	v_pk_add_f32 v[80:81], v[126:127], v[68:69]
	v_mfma_f32_32x32x16_bf16 v[0:15], v[156:159], v[204:207], v[0:15]
	v_exp_f32_e32 v82, v82
	v_exp_f32_e32 v83, v83
	v_exp_f32_e32 v84, v84
	v_exp_f32_e32 v85, v85
	v_mfma_f32_32x32x16_bf16 v[16:31], v[156:159], v[200:203], v[16:31]
	v_exp_f32_e32 v86, v86
	v_exp_f32_e32 v87, v87
	v_exp_f32_e32 v88, v88
	v_exp_f32_e32 v89, v89
	v_add_u32_e32 v62, s73, v241
	ds_read_b128 v[114:117], v62
	ds_read_b128 v[184:187], v62 offset:512
	v_mfma_f32_32x32x16_bf16 v[0:15], v[152:155], v[196:199], v[0:15]
	v_exp_f32_e32 v90, v90
	v_exp_f32_e32 v91, v91
	v_exp_f32_e32 v92, v92
	v_exp_f32_e32 v93, v93
	ds_read_b128 v[180:183], v62 offset:2048
	ds_read_b128 v[176:179], v62 offset:2560
	v_mfma_f32_32x32x16_bf16 v[16:31], v[152:155], v[192:195], v[16:31]
	v_exp_f32_e32 v94, v94
	v_exp_f32_e32 v95, v95
	v_exp_f32_e32 v96, v96
	v_exp_f32_e32 v97, v97
	ds_read_b128 v[172:175], v62 offset:4096
	ds_read_b128 v[164:167], v62 offset:4608
	v_mfma_f32_32x32x16_bf16 v[0:15], v[148:151], v[188:191], v[0:15]
	v_exp_f32_e32 v66, v98
	v_exp_f32_e32 v67, v99
	v_exp_f32_e32 v68, v112
	v_exp_f32_e32 v69, v113
	ds_read_b128 v[168:171], v62 offset:6144
	ds_read_b128 v[160:163], v62 offset:6656
	v_mfma_f32_32x32x16_bf16 v[16:31], v[148:151], v[58:61], v[16:31]
	v_exp_f32_e32 v70, v70
	v_exp_f32_e32 v71, v71
	v_exp_f32_e32 v72, v72
	v_exp_f32_e32 v73, v73
	v_mfma_f32_32x32x16_bf16 v[0:15], v[144:147], v[54:57], v[0:15]
	v_exp_f32_e32 v74, v74
	v_exp_f32_e32 v75, v75
	v_exp_f32_e32 v76, v76
	v_exp_f32_e32 v77, v77
	v_mfma_f32_32x32x16_bf16 v[16:31], v[144:147], v[50:53], v[16:31]
	v_exp_f32_e32 v78, v78
	v_exp_f32_e32 v79, v79
	v_exp_f32_e32 v80, v80
	v_exp_f32_e32 v81, v81
	v_add_u32_e32 v120, s72, v243
	s_mov_b64 s[4:5], -1
	s_and_b64 vcc, exec, s[52:53]
	s_cbranch_vccz .LBB0_525
	s_add_i32 s4, s76, -2
	s_cmp_ge_u32 s4, s74
	s_mov_b64 s[4:5], -1
	s_cbranch_scc0 .LBB0_522
	s_waitcnt vmcnt(0) lgkmcnt(0)
	s_barrier
	s_mov_b64 s[4:5], 0

.LBB0_527:
	ds_read_b64_tr_b16 v[208:209], v120 offset:24576
	ds_read_b64_tr_b16 v[210:211], v120 offset:25088
	s_waitcnt lgkmcnt(9)
	v_mfma_f32_32x32x16_bf16 v[98:113], v[114:117], v[140:143], v[32:47]
	v_add_f32_e32 v50, v82, v83
	v_add_f32_e32 v50, v84, v50
	v_add_f32_e32 v50, v85, v50
	v_add_f32_e32 v50, v86, v50
	v_add_f32_e32 v50, v87, v50
	v_cvt_pk_bf16_f32 v156, v82, v83
	v_cvt_pk_bf16_f32 v157, v84, v85
	ds_read_b64_tr_b16 v[204:205], v120 offset:28672
	ds_read_b64_tr_b16 v[206:207], v120 offset:29184
	v_add_f32_e32 v50, v88, v50
	v_add_f32_e32 v50, v89, v50
	v_add_f32_e32 v50, v90, v50
	v_add_f32_e32 v82, v91, v50
	s_waitcnt lgkmcnt(10)
	v_mfma_f32_32x32x16_bf16 v[50:65], v[184:187], v[140:143], v[32:47]
	v_cvt_pk_bf16_f32 v158, v86, v87
	v_cvt_pk_bf16_f32 v159, v88, v89
	ds_read_b64_tr_b16 v[200:201], v120 offset:25600
	ds_read_b64_tr_b16 v[202:203], v120 offset:26112
	s_waitcnt lgkmcnt(11)
	v_mfma_f32_32x32x16_bf16 v[98:113], v[180:183], v[136:139], v[98:113]
	v_add_f32_e32 v82, v92, v82
	v_add_f32_e32 v82, v93, v82
	v_add_f32_e32 v82, v94, v82
	v_add_f32_e32 v82, v95, v82
	v_cvt_pk_bf16_f32 v152, v90, v91
	v_cvt_pk_bf16_f32 v153, v92, v93
	ds_read_b64_tr_b16 v[196:197], v120 offset:29696
	ds_read_b64_tr_b16 v[198:199], v120 offset:30208
	s_waitcnt lgkmcnt(12)
	v_mfma_f32_32x32x16_bf16 v[50:65], v[176:179], v[136:139], v[50:65]
	v_add_f32_e32 v82, v96, v82
	v_add_f32_e32 v82, v97, v82
	v_add_f32_e32 v82, v66, v82
	v_add_f32_e32 v82, v67, v82
	v_cvt_pk_bf16_f32 v154, v94, v95
	v_cvt_pk_bf16_f32 v155, v96, v97
	ds_read_b64_tr_b16 v[192:193], v120 offset:26624
	ds_read_b64_tr_b16 v[194:195], v120 offset:27136
	s_waitcnt lgkmcnt(13)
	v_mfma_f32_32x32x16_bf16 v[98:113], v[172:175], v[132:135], v[98:113]
	v_add_f32_e32 v82, v68, v82
	v_add_f32_e32 v82, v69, v82
	v_add_f32_e32 v82, v70, v82
	v_add_f32_e32 v82, v71, v82
	v_cvt_pk_bf16_f32 v148, v66, v67
	v_cvt_pk_bf16_f32 v149, v68, v69
	ds_read_b64_tr_b16 v[188:189], v120 offset:30720
	ds_read_b64_tr_b16 v[190:191], v120 offset:31232
	s_waitcnt lgkmcnt(14)
	v_mfma_f32_32x32x16_bf16 v[50:65], v[164:167], v[132:135], v[50:65]
	v_add_f32_e32 v66, v72, v82
	v_add_f32_e32 v66, v73, v66
	v_add_f32_e32 v66, v74, v66
	v_add_f32_e32 v66, v75, v66
	v_cvt_pk_bf16_f32 v150, v70, v71
	v_cvt_pk_bf16_f32 v151, v72, v73
	ds_read_b64_tr_b16 v[122:123], v120 offset:27648
	ds_read_b64_tr_b16 v[124:125], v120 offset:28160
	s_waitcnt lgkmcnt(14)
	v_mfma_f32_32x32x16_bf16 v[98:113], v[168:171], v[128:131], v[98:113]
	v_add_f32_e32 v66, v76, v66
	v_add_f32_e32 v66, v77, v66
	v_add_f32_e32 v66, v78, v66
	v_add_f32_e32 v66, v79, v66
	v_cvt_pk_bf16_f32 v144, v74, v75
	v_cvt_pk_bf16_f32 v145, v76, v77
	ds_read_b64_tr_b16 v[118:119], v120 offset:31744
	ds_read_b64_tr_b16 v[120:121], v120 offset:32256
	v_mfma_f32_32x32x16_bf16 v[50:65], v[160:163], v[128:131], v[50:65]
	v_add_f32_e32 v66, v80, v66
	v_add_f32_e32 v66, v81, v66
	v_add_f32_e32 v126, 0, v66
	v_cvt_pk_bf16_f32 v146, v78, v79
	v_cvt_pk_bf16_f32 v147, v80, v81
	s_add_i32 s77, s76, 2
	s_cmp_ge_u32 s77, s71
	s_cselect_b64 s[56:57], -1, 0
	s_and_b64 vcc, exec, s[56:57]
	s_cbranch_vccnz .LBB0_529
	s_add_i32 s4, s73, s69
	s_mov_b32 s5, m0
	s_mov_b32 m0, s4
	s_nop 0
	global_load_lds_dwordx4 v[214:215], off
	s_mov_b32 m0, s5

.LBB0_541:
	v_mfma_f32_32x32x16_bf16 v[16:31], v[148:151], v[188:191], v[16:31]
	v_exp_f32_e32 v68, v68
	v_exp_f32_e32 v69, v69
	v_exp_f32_e32 v70, v70
	v_exp_f32_e32 v71, v71
	v_mfma_f32_32x32x16_bf16 v[0:15], v[144:147], v[122:125], v[0:15]
	v_exp_f32_e32 v72, v72
	v_exp_f32_e32 v73, v73
	v_exp_f32_e32 v74, v74
	v_exp_f32_e32 v75, v75
	v_mfma_f32_32x32x16_bf16 v[16:31], v[144:147], v[118:121], v[16:31]
	v_exp_f32_e32 v76, v76
	v_exp_f32_e32 v77, v77
	v_exp_f32_e32 v78, v78
	v_exp_f32_e32 v79, v79
	v_add_u32_e32 v52, s73, v243
	s_add_i32 s0, s72, 0x2000
	s_cmpk_lg_i32 s72, 0x4000
	v_add_f32_e32 v48, v48, v217
	s_cselect_b32 s0, s0, 0
	v_add_f32_e32 v48, v48, v126
	v_add_u32_e32 v49, 0x200, v49
	v_add_u32_e32 v216, 0x80, v216
	v_lshl_add_u64 v[212:213], v[212:213], 0, s[22:23]
	v_lshl_add_u64 v[214:215], v[214:215], 0, s[22:23]
	s_mov_b64 s[4:5], -1
	s_and_b64 vcc, exec, s[56:57]
	s_cbranch_vccz .LBB0_547
	s_and_b64 vcc, exec, s[52:53]
	s_cbranch_vccz .LBB0_544
	s_waitcnt vmcnt(0) lgkmcnt(0)
	s_barrier
	s_mov_b64 s[4:5], 0
